# v29: EpiRes GEMM phases: idle CUs of the tail tile's XCD stream its A/B panels (L2 warm-up) during the partial last round
# speedup vs baseline: 1.0060x; 1.0060x over previous
; #define PG8_WAIT_V(n) asm volatile("s_waitcnt vmcnt(" #n ")" ::: "memory")
; #define PG8_BAR __builtin_amdgcn_s_barrier()
;     __host__ __device__ bool next(int i, Unit& u) const {
;         const long L = (long)i * G + c; if (L >= nwg) return false;
;         int wgid = (int)L; { const int q = nwg / NXCD, r = nwg % NXCD, xcd = wgid % NXCD, off = wgid / NXCD; wgid = (xcd < r ? xcd * (q + 1) : r * (q + 1) + (xcd - r) * q) + off; }
;         const int nig = WGM * nN, gid = wgid / nig, fm = gid * WGM, gsz = (nM - fm) < WGM ? (nM - fm) : WGM;
;         u.pm = fm + ((wgid % nig) % gsz); u.pn = (wgid % nig) / gsz; return true;
; template <class Epi, class Sched, bool ALIGN_EPI = false, bool SP2 = false>
; __device__ __forceinline__ void gemm_phase(PG8_LAS unsigned char* lds, const Gemm g, const Sched& S, const Epi& E, int tid_in) {
;     ...
;     PG8_WAIT_V(0);
;     if constexpr (!ALIGN_EPI) { if (wr == 0) PG8_BAR; }
;     PG8_BAR;
.LBB0_661:
	s_waitcnt vmcnt(0)
	s_cmp_lg_u32 s94, 0x100
	s_cbranch_scc1 .Lwarm_done
	s_and_b32 s78, s20, 0xff
	s_and_b32 s79, s96, 7
	s_cmp_ge_u32 s79, s78
	s_cbranch_scc1 .Lwarm_done
	s_lshr_b32 s80, s96, 3
	s_add_i32 s80, s80, -1
	s_cmp_gt_u32 s80, 7
	s_cbranch_scc1 .Lwarm_done
	s_lshr_b32 s81, s20, 3
	s_and_b32 s54, s20, 7
	s_mul_i32 s55, s79, s81
	s_min_u32 s54, s79, s54
	s_add_i32 s55, s55, s54
	s_lshr_b32 s54, s20, 8
	s_lshl_b32 s54, s54, 5
	s_add_i32 s55, s55, s54
	s_lshr_b32 s54, s55, 5
	s_and_b32 s55, s55, 31
	s_lshl_b32 s54, s54, 3
	s_sub_i32 s62, s60, s54
	s_min_i32 s62, s62, 8
	s_ff1_i32_b32 s63, s62
	s_lshr_b32 s64, s55, s63
	s_add_i32 s62, s62, -1
	s_and_b32 s55, s55, s62
	s_add_i32 s54, s54, s55
	s_lshr_b32 s65, s42, 3
	s_mul_i32 s55, s65, s80
	s_mul_i32 s62, s42, s54
	s_mul_hi_u32 s63, s42, s54
	s_mul_i32 s81, s43, s54
	s_add_i32 s63, s63, s81
	s_add_u32 s62, s62, s18
	s_addc_u32 s63, s63, s19
	s_add_u32 s62, s62, s55
	s_addc_u32 s63, s63, 0
	s_mul_i32 s68, s42, s64
	s_mul_hi_u32 s69, s42, s64
	s_mul_i32 s81, s43, s64
	s_add_i32 s69, s69, s81
	s_add_u32 s68, s68, s8
	s_addc_u32 s69, s69, s9
	s_add_u32 s68, s68, s55
	s_addc_u32 s69, s69, 0
	v_mbcnt_lo_u32_b32 v2, -1, 0
	v_mbcnt_hi_u32_b32 v2, -1, v2
	v_add_u32_e32 v2, s84, v2
	v_lshlrev_b32_e32 v2, 4, v2
	s_lshr_b32 s54, s65, 13
.Lwarm_loop:
	global_load_dwordx4 v[4:7], v2, s[62:63]
	global_load_dwordx4 v[8:11], v2, s[68:69]
	v_add_u32_e32 v2, 0x2000, v2
	s_add_i32 s54, s54, -1
	s_cmp_lg_u32 s54, 0
	s_cbranch_scc1 .Lwarm_loop
	s_waitcnt vmcnt(0)
.Lwarm_done:
	v_readlane_b32 s78, v254, 46
	v_readlane_b32 s80, v254, 55
	v_readlane_b32 s54, v254, 58
	v_readlane_b32 s62, v254, 62
	v_readlane_b32 s79, v254, 47
	v_readlane_b32 s81, v254, 56
	v_readlane_b32 s55, v254, 59
	v_readlane_b32 s63, v254, 63
	s_movk_i32 s64, 0x6000
	s_mov_b32 s40, s92
	v_readlane_b32 s65, v255, 9
	s_mov_b64 s[68:69], s[88:89]
	s_barrier
